# layer-1 FFN1 weight conversion (transpose items 0..4223) done by the 128 workgroups idle in the last round of layer-0 FFN2 up; layer-1 prologue skips them
# baseline (speedup 1.0000x reference)
; __device__ __forceinline__ void prologue(Frame& F, const Args& A, int l) {
;     ...
;     for (int it = gw; it < NITEMS; it += NGW) {
;         int r = it, si, sci = -1, K = DM, N = FFH, rs = 128, off = 0, nblk = 32; size_t so = oFF, dsto;
;         if (r < 6 * 1408) { const int w = r / 1408; r -= w * 1408; const int second = w >= 3, t = w % 3;
.Lpro_rot_ok:
	v_readlane_b32 vcc_lo, v255, 18
	s_nop 1
	s_cmp_eq_u32 vcc_lo, 0
	s_cbranch_scc1 .Lpro_l0
	s_addk_i32 s13, 0x1000
	s_cmpk_lt_i32 s13, 0x1080
	s_cbranch_scc0 .Lpro_l0
	s_addk_i32 s13, 0x800

; #define LAS __attribute__((address_space(3)))
; __device__ __forceinline__ void transpose_item(const float* W, int K, int N, bf16* WT, int rs, int off, const float* sc, LAS float* scr, int item, int nblk, int lane, int swp) {
;     const int kb = item / nblk, nb = item % nblk, k0 = 64 * kb, n0 = 32 * nb;
;     const int n = n0 + (lane & 31);
; __device__ __forceinline__ void prologue(Frame& F, const Args& A, int l) {
;     LAS float* scr = (LAS float*)(F.lds + F.wave * 16384);
;     const int gw = F.vcu * NWAVES + F.wave, NGW = F.G * NWAVES;
;     unsigned char* ws = F.ws;
;     const size_t oFF = (size_t)l * DM * FFH, oDD = (size_t)l * DM * DM;
;     constexpr int I_GU = 16 * 88, I_DN = 44 * 32, I_IN = 16 * 120, I_SQ = 16 * 32;
;     constexpr int NITEMS = 6 * 1408 + I_IN + 4 * I_SQ;
;     for (int it = gw; it < NITEMS; it += NGW) {
;         int r = it, si, sci = -1, K = DM, N = FFH, rs = 128, off = 0, nblk = 32; size_t so = oFF, dsto;
.LBB0_1228:
	v_readlane_b32 vcc_lo, v255, 18
	s_nop 1
	s_cmp_lg_u32 vcc_lo, 0
	s_cbranch_scc1 .Lpi_exit
	s_cmpk_lt_u32 s83, 0x80
	s_cbranch_scc1 .Lpi_exit
	v_readlane_b32 s90, v255, 24
	v_readlane_b32 s91, v255, 25
	s_nop 1
	v_readlane_b32 s4, v255, 20
	v_readlane_b32 s6, v255, 22
	v_readlane_b32 s7, v255, 23
	s_mov_b32 s1, s83
	s_mov_b32 s0, s56
	s_mov_b32 s2, s69
	v_readlane_b32 s5, v255, 21
	s_mov_b64 s[10:11], s[6:7]
	v_mov_b32_e32 v9, v203
	s_and_b32 s4, s0, 7
	s_cmp_lg_u32 s4, 0
	v_readfirstlane_b32 s4, v9
	s_cbranch_scc1 .Lpi_b8
	s_ashr_i32 s6, s1, 31
	s_lshr_b32 s6, s6, 29
	s_add_i32 s6, s1, s6
	s_ashr_i32 s7, s6, 3
	s_and_b32 s6, s6, -8
	s_ashr_i32 s5, s0, 3
	s_sub_i32 s1, s1, s6
	s_mul_i32 s1, s5, s1
	s_add_i32 s1, s1, s7
.Lpi_b8:
	s_ashr_i32 s35, s4, 6
	s_lshl_b32 s36, s1, 3
	s_mov_b32 s4, 1
	s_add_i32 s34, s83, 0xffffff80
	s_lshl_b32 s34, s34, 3
	s_add_i32 s34, s34, s35
	s_movk_i32 s12, 0x400
	s_lshl_b32 s4, s4, 10
	v_and_b32_e32 v20, 63, v9
	s_cmpk_gt_i32 s34, 0x107f
	v_readlane_b32 s5, v255, 19
	s_cbranch_scc1 .Lpi_exit
	s_lshl_b32 s8, s35, 14
	s_mul_i32 s68, s4, 0xb00
	s_add_i32 s2, s2, s8
	v_and_b32_e32 v21, 31, v9
	v_lshrrev_b32_e32 v22, 5, v20
	v_and_b32_e32 v2, 7, v9
	v_lshrrev_b32_e32 v23, 3, v20
	s_mov_b32 s5, s69
	s_mov_b64 s[6:7], s[68:69]
	s_mul_i32 s68, s4, 0xe08
	v_lshl_add_u32 v0, v21, 2, s2
	v_mul_u32_u24_e32 v1, 0x84, v22
	v_lshlrev_b32_e32 v8, 3, v2
	v_mul_u32_u24_e32 v2, 0x420, v2
	v_lshlrev_b32_e32 v3, 2, v23
	s_lshl_b64 s[14:15], s[4:5], 10
	s_mov_b64 s[16:17], s[68:69]
	v_add3_u32 v24, s2, v2, v3
	v_or_b32_e32 v25, 8, v23
	v_or_b32_e32 v26, 16, v23
	v_or_b32_e32 v27, 24, v23
	v_add_u32_e32 v28, v0, v1
	v_lshlrev_b32_e32 v192, 1, v8
	s_lshr_b32 s13, s12, 1
	s_add_i32 s13, s34, s13
	s_cmp_ge_i32 s13, s12
	s_cbranch_scc0 .Lpi_Lpro_rot_ok
	s_sub_i32 s13, s13, s12

; __device__ __forceinline__ unsigned cvt_pk_bf16(float lo, float hi) { const f32x2cv v = {lo, hi}; const bf16x2cv b = __builtin_convertvector(v, bf16x2cv); return __builtin_bit_cast(unsigned, b); }
; #define LAS __attribute__((address_space(3)))
; __device__ __forceinline__ void transpose_item(const float* W, int K, int N, bf16* WT, int rs, int off, const float* sc, LAS float* scr, int item, int nblk, int lane, int swp) {
;     ...
;     for (int j = 0; j < 4; ++j) { const int nn = (lane >> 3) + 8 * j; const LAS float* s = scr + (8 * c) * 33 + nn;
;         v4u o; o.x = cvt_pk_bf16(s[0 * 33] * s0[0], s[1 * 33] * s0[1]); o.y = cvt_pk_bf16(s[2 * 33] * s0[2], s[3 * 33] * s0[3]); o.z = cvt_pk_bf16(s[4 * 33] * s1[0], s[5 * 33] * s1[1]); o.w = cvt_pk_bf16(s[6 * 33] * s1[2], s[7 * 33] * s1[3]);
;         const int ng = n0 + nn, t256 = ng >> 8, ts256 = (t256 == 2) ? 7 : (t256 == 7) ? 2 : t256, dr = swp ? ts256 * 256 + (ng & 255) : (ng / 128) * rs + off + (ng % 128);
;         *(v4u*)(WT + (size_t)dr * K + k0 + 8 * c) = o; }
; __device__ __forceinline__ void prologue(Frame& F, const Args& A, int l) {
;     ...
;     for (int it = gw; it < NITEMS; it += NGW) {
.Lpi_b10:
	s_waitcnt lgkmcnt(0)
	v_pk_mul_f32 v[4:5], v[4:5], v[18:19]
	v_pk_mul_f32 v[6:7], v[6:7], v[16:17]
	v_pk_mul_f32 v[0:1], v[0:1], v[14:15]
	v_cvt_pk_bf16_f32 v4, v4, v5
	v_cvt_pk_bf16_f32 v5, v6, v7
	v_cvt_pk_bf16_f32 v6, v0, v1
	v_pk_mul_f32 v[0:1], v[2:3], v[12:13]
	s_add_i32 s13, s13, s12
	v_cvt_pk_bf16_f32 v7, v0, v1
	v_mad_i64_i32 v[0:1], s[18:19], s18, v29, 0
	v_lshl_add_u64 v[0:1], v[0:1], 1, v[10:11]
	flat_store_dwordx4 v[0:1], v[4:7]
	s_waitcnt lgkmcnt(0)
	s_cmpk_gt_i32 s13, 0x107f
	s_cbranch_scc1 .Lpi_exit

; __device__ __forceinline__ unsigned xb_ld_u(unsigned* p) { return (unsigned)__builtin_amdgcn_readfirstlane((int)__hip_atomic_load(p, RLX_AGENT)); }
; __device__ __forceinline__ unsigned xb_add_u(unsigned* p, unsigned v, int lane) { unsigned r = 0u; if (lane == 0) r = __hip_atomic_fetch_add(p, v, RLX_AGENT); return (unsigned)__builtin_amdgcn_readfirstlane((int)r); }
; __device__ __forceinline__ unsigned xb_xcc_id() { return (unsigned)__builtin_amdgcn_s_getreg((3 << 11) | 20) & 0xFu; }
; __device__ __forceinline__ void transpose_item(const float* W, int K, int N, bf16* WT, int rs, int off, const float* sc, LAS float* scr, int item, int nblk, int lane, int swp) {
;     ...
;         const int ng = n0 + nn, t256 = ng >> 8, ts256 = (t256 == 2) ? 7 : (t256 == 7) ? 2 : t256, dr = swp ? ts256 * 256 + (ng & 255) : (ng / 128) * rs + off + (ng % 128);
;         *(v4u*)(WT + (size_t)dr * K + k0 + 8 * c) = o; }
; __device__ __forceinline__ void xcd_barrier(unsigned* bar, volatile __attribute__((address_space(3))) unsigned* st, int wave, int lane) {
;     asm volatile("s_waitcnt vmcnt(0)" ::: "memory");
;     __syncthreads();
;     if (wave == 0) {
;         __builtin_amdgcn_s_waitcnt(0);
;         const unsigned x = xb_xcc_id();
;         unsigned nloc = (unsigned)__builtin_amdgcn_readfirstlane((int)st[0]), nx = (unsigned)__builtin_amdgcn_readfirstlane((int)st[1]);
;         if (nloc == 0u) {
;             const unsigned G = gridDim.x; unsigned sp = 0u;
;             (void)xb_add_u(&bar[XB_XCNT(x)], 1u, lane);
;             for (;;) { unsigned sum = 0u, cnt = 0u, mine = 0u;
; #pragma unroll
;                 for (unsigned j = 0; j < 16; ++j) { const unsigned c = xb_ld_u(&bar[XB_XCNT(j)]); sum += c; cnt += (c > 0u) ? 1u : 0u; mine = (j == x) ? c : mine; }
;                 nloc = mine > 0u ? mine : 1u; nx = cnt > 0u ? cnt : 1u;
;                 if (sum == G) break;
;                 __builtin_amdgcn_s_sleep(1);
;                 if (++sp > XB_SPIN_CAP) { if (lane == 0) atomicAdd(&bar[XB_TMO], 1u); break; } }
;             if (lane == 0) { st[0] = nloc; st[1] = nx; }
;         }
;         const unsigned old = xb_add_u(&bar[XB_XSUB(x)], 1u, lane), gen = old / nloc;
.Lpi_b47:
	s_andn2_b64 vcc, exec, s[20:21]
	s_cbranch_vccnz .Lpi_b10
	s_ashr_i32 s2, s19, 3
	s_and_b32 s8, s39, 0xffffff00
	s_cmp_lg_u32 s2, 7
	s_cselect_b32 s8, s8, 0x200
	s_cmp_lg_u32 s2, 2
	s_cselect_b32 s2, s8, 0x700
	v_or_b32_sdwa v29, s2, v30 dst_sel:DWORD dst_unused:UNUSED_PAD src0_sel:DWORD src1_sel:BYTE_0
	s_branch .Lpi_b10
.Lpi_exit:
	v_readlane_b32 s4, v255, 20
	v_readlane_b32 s6, v255, 22
	v_readlane_b32 s7, v255, 23
	s_mov_b32 s68, s69
	s_mov_b64 s[10:11], s[6:7]
	v_mov_b32_e32 v0, v203
	s_waitcnt vmcnt(0)
	v_readlane_b32 s5, v255, 21
	v_readfirstlane_b32 s0, v0
	s_cmp_gt_u32 s0, 63
	s_waitcnt lgkmcnt(0)
	s_barrier
	s_cbranch_scc1 .LBB0_1296
	s_add_u32 s8, s10, 0xe200000
	s_addc_u32 s9, s11, 0
	s_add_i32 s1, s68, 0x22000
	v_and_b32_e32 v1, 63, v0
	v_mov_b32_e32 v0, s1
	s_waitcnt vmcnt(0) expcnt(0) lgkmcnt(0)
	s_getreg_b32 s0, hwreg(HW_REG_XCC_ID, 0, 4)
	ds_read_b32 v0, v0
	s_add_i32 s68, s68, 0x22004
	s_and_b32 s0, s0, 15
	s_waitcnt lgkmcnt(0)
	v_readfirstlane_b32 s2, v0
	v_mov_b32_e32 v0, s68
	ds_read_b32 v0, v0
	s_cmp_lg_u32 s2, 0
	v_mov_b32_e32 v2, s2
	s_waitcnt lgkmcnt(0)
	v_readfirstlane_b32 s4, v0
	s_nop 1
	v_mov_b32_e32 v0, s4
	v_cmp_eq_u32_e64 s[4:5], 0, v1
	s_cbranch_scc1 .LBB0_1246
	v_cmp_ne_u32_e32 vcc, 0, v1
	s_and_saveexec_b64 s[6:7], s[4:5]
	s_cbranch_execz .LBB0_1232
	s_lshl_b32 s2, s0, 8
	s_add_u32 s12, s8, s2
	s_addc_u32 s13, s9, 0
	v_mov_b64_e32 v[2:3], s[12:13]
	flat_atomic_add v[2:3], v244 offset:1024
